# plus: D2 K/Q operand loads software-pipelined one k-step ahead (two register sets); D1 next-item row loads kept in flight behind counted vmcnt
# speedup vs baseline: 1.0052x; 1.0052x over previous
; #define MFMA32(a, b, c) __builtin_amdgcn_mfma_f32_32x32x16_bf16((a), (b), (c), 0, 0, 0)
; DI void d2_chunk(const Params& P, int l, int chunk, LAS float* Nm, LAS float* gs, int lane_in) {
;     ...
; #pragma unroll 2
;         for (int kk = 0; kk < 8; ++kk) {
;             const bf16x8 k0 = *(const bf16x8*)(Kc + r * 128 + 16 * kk + 8 * hi), k1 = *(const bf16x8*)(Kc + (32 + r) * 128 + 16 * kk + 8 * hi);
;             const bf16x8 q0 = *(const bf16x8*)(Qc + r * 128 + 16 * kk + 8 * hi), q1 = *(const bf16x8*)(Qc + (32 + r) * 128 + 16 * kk + 8 * hi);
;             kk00 = MFMA32(k0, k0, kk00); kk10 = MFMA32(k0, k1, kk10); kk11 = MFMA32(k1, k1, kk11);
;             qk00 = MFMA32(k0, q0, qk00); qk10 = MFMA32(k0, q1, qk10); qk11 = MFMA32(k1, q1, qk11);
;         }
.LBB0_384:
	s_mov_b32 s4, 0x1d100000
	v_add_co_u32_e32 v118, vcc, s4, v100
	s_mov_b32 s4, 0x1d102000
	s_nop 0
	v_addc_co_u32_e32 v119, vcc, 0, v101, vcc
	v_add_co_u32_e32 v120, vcc, s4, v100
	s_mov_b32 s4, 0x1b100000
	s_nop 0
	v_addc_co_u32_e32 v121, vcc, 0, v101, vcc
	v_add_co_u32_e32 v122, vcc, s4, v100
	s_mov_b32 s4, 0x1b102000
	s_nop 0
	v_addc_co_u32_e32 v123, vcc, 0, v101, vcc
	v_add_co_u32_e32 v124, vcc, s4, v100
	s_nop 1
	v_addc_co_u32_e32 v125, vcc, 0, v101, vcc
	global_load_dwordx4 v[102:105], v[118:119], off
	global_load_dwordx4 v[106:109], v[120:121], off
	global_load_dwordx4 v[110:113], v[122:123], off
	global_load_dwordx4 v[114:117], v[124:125], off
	global_load_dwordx4 v[126:129], v[118:119], off offset:32
	global_load_dwordx4 v[130:133], v[120:121], off offset:32
	global_load_dwordx4 v[134:137], v[122:123], off offset:32
	global_load_dwordx4 v[138:141], v[124:125], off offset:32
	s_waitcnt vmcnt(4)
	v_mfma_f32_32x32x16_bf16 v[0:15], v[102:105], v[102:105], v[0:15]
	v_mfma_f32_32x32x16_bf16 v[48:63], v[102:105], v[106:109], v[48:63]
	v_mfma_f32_32x32x16_bf16 v[16:31], v[106:109], v[106:109], v[16:31]
	v_mfma_f32_32x32x16_bf16 v[80:95], v[102:105], v[110:113], v[80:95]
	v_mfma_f32_32x32x16_bf16 v[64:79], v[102:105], v[114:117], v[64:79]
	v_mfma_f32_32x32x16_bf16 v[32:47], v[106:109], v[114:117], v[32:47]
	global_load_dwordx4 v[102:105], v[118:119], off offset:64
	global_load_dwordx4 v[106:109], v[120:121], off offset:64
	global_load_dwordx4 v[110:113], v[122:123], off offset:64
	global_load_dwordx4 v[114:117], v[124:125], off offset:64
	s_waitcnt vmcnt(4)
	v_mfma_f32_32x32x16_bf16 v[0:15], v[126:129], v[126:129], v[0:15]
	v_mfma_f32_32x32x16_bf16 v[48:63], v[126:129], v[130:133], v[48:63]
	v_mfma_f32_32x32x16_bf16 v[16:31], v[130:133], v[130:133], v[16:31]
	v_mfma_f32_32x32x16_bf16 v[80:95], v[126:129], v[134:137], v[80:95]
	v_mfma_f32_32x32x16_bf16 v[64:79], v[126:129], v[138:141], v[64:79]
	v_mfma_f32_32x32x16_bf16 v[32:47], v[130:133], v[138:141], v[32:47]
	global_load_dwordx4 v[126:129], v[118:119], off offset:96
	global_load_dwordx4 v[130:133], v[120:121], off offset:96
	global_load_dwordx4 v[134:137], v[122:123], off offset:96
	global_load_dwordx4 v[138:141], v[124:125], off offset:96
	s_waitcnt vmcnt(4)
	v_mfma_f32_32x32x16_bf16 v[0:15], v[102:105], v[102:105], v[0:15]
	v_mfma_f32_32x32x16_bf16 v[48:63], v[102:105], v[106:109], v[48:63]
	v_mfma_f32_32x32x16_bf16 v[16:31], v[106:109], v[106:109], v[16:31]
	v_mfma_f32_32x32x16_bf16 v[80:95], v[102:105], v[110:113], v[80:95]
	v_mfma_f32_32x32x16_bf16 v[64:79], v[102:105], v[114:117], v[64:79]
	v_mfma_f32_32x32x16_bf16 v[32:47], v[106:109], v[114:117], v[32:47]
	global_load_dwordx4 v[102:105], v[118:119], off offset:128
	global_load_dwordx4 v[106:109], v[120:121], off offset:128
	global_load_dwordx4 v[110:113], v[122:123], off offset:128
	global_load_dwordx4 v[114:117], v[124:125], off offset:128
	s_waitcnt vmcnt(4)
	v_mfma_f32_32x32x16_bf16 v[0:15], v[126:129], v[126:129], v[0:15]
	v_mfma_f32_32x32x16_bf16 v[48:63], v[126:129], v[130:133], v[48:63]
	v_mfma_f32_32x32x16_bf16 v[16:31], v[130:133], v[130:133], v[16:31]
	v_mfma_f32_32x32x16_bf16 v[80:95], v[126:129], v[134:137], v[80:95]
	v_mfma_f32_32x32x16_bf16 v[64:79], v[126:129], v[138:141], v[64:79]
	v_mfma_f32_32x32x16_bf16 v[32:47], v[130:133], v[138:141], v[32:47]
	global_load_dwordx4 v[126:129], v[118:119], off offset:160
	global_load_dwordx4 v[130:133], v[120:121], off offset:160
	global_load_dwordx4 v[134:137], v[122:123], off offset:160
	global_load_dwordx4 v[138:141], v[124:125], off offset:160
	s_waitcnt vmcnt(4)
	v_mfma_f32_32x32x16_bf16 v[0:15], v[102:105], v[102:105], v[0:15]
	v_mfma_f32_32x32x16_bf16 v[48:63], v[102:105], v[106:109], v[48:63]
	v_mfma_f32_32x32x16_bf16 v[16:31], v[106:109], v[106:109], v[16:31]
	v_mfma_f32_32x32x16_bf16 v[80:95], v[102:105], v[110:113], v[80:95]
	v_mfma_f32_32x32x16_bf16 v[64:79], v[102:105], v[114:117], v[64:79]
	v_mfma_f32_32x32x16_bf16 v[32:47], v[106:109], v[114:117], v[32:47]
	global_load_dwordx4 v[102:105], v[118:119], off offset:192
	global_load_dwordx4 v[106:109], v[120:121], off offset:192
	global_load_dwordx4 v[110:113], v[122:123], off offset:192
	global_load_dwordx4 v[114:117], v[124:125], off offset:192
	s_waitcnt vmcnt(4)
	v_mfma_f32_32x32x16_bf16 v[0:15], v[126:129], v[126:129], v[0:15]
	v_mfma_f32_32x32x16_bf16 v[48:63], v[126:129], v[130:133], v[48:63]
	v_mfma_f32_32x32x16_bf16 v[16:31], v[130:133], v[130:133], v[16:31]
	v_mfma_f32_32x32x16_bf16 v[80:95], v[126:129], v[134:137], v[80:95]
	v_mfma_f32_32x32x16_bf16 v[64:79], v[126:129], v[138:141], v[64:79]
	v_mfma_f32_32x32x16_bf16 v[32:47], v[130:133], v[138:141], v[32:47]
	global_load_dwordx4 v[126:129], v[118:119], off offset:224
	global_load_dwordx4 v[130:133], v[120:121], off offset:224
	global_load_dwordx4 v[134:137], v[122:123], off offset:224
	global_load_dwordx4 v[138:141], v[124:125], off offset:224
	s_waitcnt vmcnt(4)
	v_mfma_f32_32x32x16_bf16 v[0:15], v[102:105], v[102:105], v[0:15]
	v_mfma_f32_32x32x16_bf16 v[48:63], v[102:105], v[106:109], v[48:63]
	v_mfma_f32_32x32x16_bf16 v[16:31], v[106:109], v[106:109], v[16:31]
	v_mfma_f32_32x32x16_bf16 v[80:95], v[102:105], v[110:113], v[80:95]
	v_mfma_f32_32x32x16_bf16 v[64:79], v[102:105], v[114:117], v[64:79]
	v_mfma_f32_32x32x16_bf16 v[32:47], v[106:109], v[114:117], v[32:47]
	s_waitcnt vmcnt(0)
	v_mfma_f32_32x32x16_bf16 v[0:15], v[126:129], v[126:129], v[0:15]
	v_mfma_f32_32x32x16_bf16 v[48:63], v[126:129], v[130:133], v[48:63]
	v_mfma_f32_32x32x16_bf16 v[16:31], v[130:133], v[130:133], v[16:31]
	v_mfma_f32_32x32x16_bf16 v[80:95], v[126:129], v[134:137], v[80:95]
	v_mfma_f32_32x32x16_bf16 v[64:79], v[126:129], v[138:141], v[64:79]
	v_mfma_f32_32x32x16_bf16 v[32:47], v[130:133], v[138:141], v[32:47]
	v_lshl_add_u32 v243, v96, 2, s13
	ds_read2st64_b32 v[100:101], v243 offset1:1
	v_lshlrev_b32_e32 v168, 2, v179
	v_cmp_le_i32_e64 s[4:5], v168, v96
	v_mov_b32_e32 v114, 0
	v_lshl_add_u32 v102, v168, 2, s13
	v_mov_b32_e32 v115, 0
	s_and_saveexec_b64 s[0:1], s[4:5]
	s_cbranch_execz .LBB0_387
	ds_read_b32 v99, v102
	s_waitcnt lgkmcnt(0)
	v_sub_f32_e32 v99, v100, v99
	v_mul_f32_e32 v99, 0x3fb8aa3b, v99
	v_exp_f32_e32 v115, v99
